# v59 + P3 passC chunk loop: all 20 later global loads of a chunk (OL tiles, second QG pair, gnorm, ZG tiles) issued at the chunk top into v152-215, consumers renamed, every vmcnt recomputed (was 4+4 se
# baseline (speedup 1.0000x reference)
; #define LAS __attribute__((address_space(3)))
; #define MFMA16(a, b, c) __builtin_amdgcn_mfma_f32_16x16x32_bf16((a), (b), (c), 0, 0, 0)
; DI void hgrn_passC(LAS unsigned char* lds, const bf16* QG, const float* OL, const float* DS, const float* DSC, const bf16* ZG, const float* gnorm, bf16* OG, float* state_out, int bid, int G, int tid) {
;     ...
;         for (int c = wave; c < 32; c += 8) {
;             bf16x8 a[4];
; #pragma unroll
;             for (int s = 0; s < 4; ++s) a[s] = *(const bf16x8*)(QG + (size_t)(t0 + 16 * c + lr) * D + cb + 32 * s + 8 * g);
;             f32x4 o[8]; float ssq[4] = {0.f, 0.f, 0.f, 0.f};
; #pragma unroll
;             for (int vt = 0; vt < 8; ++vt) {
;                 f32x4 acc = *(const f32x4*)(OL + ((((size_t)(h * 16 + sc) * 32 + c) * 8 + vt) * 64 + lane) * 4);
; #pragma unroll
;                 for (int s = 0; s < 4; ++s) acc = MFMA16(a[s], *(const LAS bf16x8*)(lds + HC_SINT + (16 * vt + lr) * 272 + 64 * s + 16 * g), acc);
;                 o[vt] = acc;
; #pragma unroll
;                 for (int i = 0; i < 4; ++i) ssq[i] += acc[i] * acc[i];
;             }
.LBB0_461:
	v_lshl_add_u64 v[64:65], s[10:11], 0, v[44:45]
	v_add_co_u32_e32 v122, vcc, 0x1cc00000, v64
	v_lshl_add_u64 v[46:47], s[10:11], 0, v[34:35]
	s_nop 0
	v_addc_co_u32_e32 v123, vcc, 0, v65, vcc
	ds_read_b128 v[0:3], v74
	ds_read_b128 v[4:7], v74 offset:64
	ds_read_b128 v[8:11], v74 offset:4352
	ds_read_b128 v[12:15], v74 offset:4416
	ds_read_b128 v[52:55], v74 offset:8704
	ds_read_b128 v[56:59], v74 offset:8768
	ds_read_b128 v[60:63], v74 offset:13056
	ds_read_b128 v[78:81], v74 offset:13120
	ds_read_b128 v[82:85], v74 offset:17408
	ds_read_b128 v[86:89], v74 offset:17472
	ds_read_b128 v[90:93], v74 offset:21760
	ds_read_b128 v[94:97], v74 offset:21824
	ds_read_b128 v[98:101], v74 offset:26112
	ds_read_b128 v[102:105], v74 offset:26176
	global_load_dwordx4 v[106:109], v[46:47], off offset:-128
	global_load_dwordx4 v[110:113], v[46:47], off offset:-64
	global_load_dwordx4 v[114:117], v[122:123], off
	global_load_dwordx4 v[118:121], v[122:123], off offset:1024
	v_add_co_u32_e64 v124, s[4:5], s3, v64
	v_add_u32_e32 v126, 0x8800, v75
	s_nop 0
	v_addc_co_u32_e64 v125, s[4:5], 0, v65, s[4:5]
	v_lshl_add_u64 v[64:65], s[10:11], 0, v[36:37]
	global_load_dwordx4 v[152:155], v[122:123], off offset:2048
	global_load_dwordx4 v[156:159], v[122:123], off offset:3072
	global_load_dwordx4 v[160:163], v[124:125], off
	global_load_dwordx4 v[164:167], v[124:125], off offset:1024
	global_load_dwordx4 v[168:171], v[124:125], off offset:2048
	global_load_dwordx4 v[172:175], v[124:125], off offset:3072
	global_load_dwordx4 v[176:179], v[46:47], off
	global_load_dwordx4 v[180:183], v[46:47], off offset:64
	global_load_dword v184, v[28:29], off
	global_load_dword v185, v[28:29], off offset:64
	global_load_dword v186, v[28:29], off offset:128
	global_load_dword v187, v[28:29], off offset:192
	global_load_dword v188, v[28:29], off offset:256
	global_load_dword v189, v[28:29], off offset:320
	global_load_dword v190, v[28:29], off offset:384
	global_load_dword v191, v[28:29], off offset:448
	s_mov_b32 s100, s23
	s_mov_b32 s101, 0
	v_lshl_add_u64 v[192:193], v[64:65], 0, s[100:101]
	global_load_dwordx4 v[200:203], v[192:193], off
	v_lshl_add_u64 v[194:195], s[10:11], 0, v[42:43]
	v_lshl_add_u64 v[194:195], v[194:195], 0, s[100:101]
	global_load_dwordx4 v[204:207], v[194:195], off
	v_lshl_add_u64 v[196:197], s[10:11], 0, v[40:41]
	v_lshl_add_u64 v[196:197], v[196:197], 0, s[100:101]
	global_load_dwordx4 v[208:211], v[196:197], off
	v_lshl_add_u64 v[198:199], s[10:11], 0, v[38:39]
	v_lshl_add_u64 v[198:199], v[198:199], 0, s[100:101]
	global_load_dwordx4 v[212:215], v[198:199], off
	v_add_u32_e32 v127, 0x8c00, v75
	s_add_i32 s34, s34, 8
	v_lshl_add_u64 v[34:35], v[34:35], 0, s[38:39]
	v_lshl_add_u64 v[36:37], v[36:37], 0, s[38:39]
	v_lshl_add_u64 v[44:45], v[44:45], 0, s[40:41]
	s_cmp_gt_i32 s34, 23
	s_waitcnt vmcnt(21) lgkmcnt(13)
	v_mfma_f32_16x16x32_bf16 v[0:3], v[106:109], v[0:3], v[114:117]
	s_nop 2
	s_waitcnt vmcnt(20) lgkmcnt(11)
	v_mfma_f32_16x16x32_bf16 v[8:11], v[106:109], v[8:11], v[118:121]
	s_nop 2
	v_mfma_f32_16x16x32_bf16 v[0:3], v[110:113], v[4:7], v[0:3]
	s_waitcnt lgkmcnt(10)
	v_mfma_f32_16x16x32_bf16 v[4:7], v[110:113], v[12:15], v[8:11]
	s_waitcnt vmcnt(19) lgkmcnt(9)
	v_mfma_f32_16x16x32_bf16 v[52:55], v[106:109], v[52:55], v[152:155]
	s_nop 2
	s_waitcnt vmcnt(18) lgkmcnt(7)
	v_mfma_f32_16x16x32_bf16 v[60:63], v[106:109], v[60:63], v[156:159]
	s_nop 2
	v_mfma_f32_16x16x32_bf16 v[8:11], v[110:113], v[56:59], v[52:55]
	s_waitcnt lgkmcnt(6)
	v_mfma_f32_16x16x32_bf16 v[52:55], v[110:113], v[78:81], v[60:63]
	s_waitcnt vmcnt(17) lgkmcnt(5)
	v_mfma_f32_16x16x32_bf16 v[82:85], v[106:109], v[82:85], v[160:163]
	s_nop 2
	s_waitcnt vmcnt(16) lgkmcnt(3)
	v_mfma_f32_16x16x32_bf16 v[90:93], v[106:109], v[90:93], v[164:167]
	s_nop 2
	v_mfma_f32_16x16x32_bf16 v[56:59], v[110:113], v[86:89], v[82:85]
	s_waitcnt lgkmcnt(2)
	v_mfma_f32_16x16x32_bf16 v[60:63], v[110:113], v[94:97], v[90:93]
	s_waitcnt vmcnt(15) lgkmcnt(1)
	v_mfma_f32_16x16x32_bf16 v[98:101], v[106:109], v[98:101], v[168:171]
	s_nop 2
	ds_read_b128 v[114:117], v74 offset:30464
	ds_read_b128 v[122:125], v74 offset:30528
	ds_read_b128 v[78:81], v74 offset:128
	ds_read_b128 v[82:85], v74 offset:192
	s_waitcnt lgkmcnt(4)
	v_mfma_f32_16x16x32_bf16 v[86:89], v[110:113], v[102:105], v[98:101]
	v_mov_b64_e32 v[46:47], s[22:23]
	s_waitcnt vmcnt(14) lgkmcnt(3)
	v_mfma_f32_16x16x32_bf16 v[106:109], v[106:109], v[114:117], v[172:175]
	s_waitcnt lgkmcnt(2)
	v_mfma_f32_16x16x32_bf16 v[94:97], v[110:113], v[122:125], v[106:109]
	s_waitcnt vmcnt(13) lgkmcnt(1)
	v_mfma_f32_16x16x32_bf16 v[0:3], v[176:179], v[78:81], v[0:3]
	ds_read_b128 v[78:81], v74 offset:4480
	ds_read_b128 v[98:101], v74 offset:4544
	s_waitcnt lgkmcnt(1)
	v_mfma_f32_16x16x32_bf16 v[4:7], v[176:179], v[78:81], v[4:7]
	ds_read_b128 v[78:81], v74 offset:8832
	ds_read_b128 v[102:105], v74 offset:8896
	s_waitcnt lgkmcnt(1)
	v_mfma_f32_16x16x32_bf16 v[78:81], v[176:179], v[78:81], v[8:11]
	s_nop 2
	ds_read_b128 v[8:11], v74 offset:13184
	ds_read_b128 v[106:109], v74 offset:13248
	s_waitcnt lgkmcnt(1)
	v_mfma_f32_16x16x32_bf16 v[52:55], v[176:179], v[8:11], v[52:55]
	ds_read_b128 v[8:11], v74 offset:17536
	ds_read_b128 v[110:113], v74 offset:17600
	s_waitcnt lgkmcnt(1)
	v_mfma_f32_16x16x32_bf16 v[56:59], v[176:179], v[8:11], v[56:59]
	ds_read_b128 v[8:11], v74 offset:21888
	ds_read_b128 v[114:117], v74 offset:21952
	s_waitcnt lgkmcnt(1)
	v_mfma_f32_16x16x32_bf16 v[60:63], v[176:179], v[8:11], v[60:63]
	ds_read_b128 v[8:11], v74 offset:26240
	ds_read_b128 v[118:121], v74 offset:26304
	s_waitcnt lgkmcnt(1)
; #define LAS __attribute__((address_space(3)))
; #define MFMA16(a, b, c) __builtin_amdgcn_mfma_f32_16x16x32_bf16((a), (b), (c), 0, 0, 0)
; DI void hgrn_passC(LAS unsigned char* lds, const bf16* QG, const float* OL, const float* DS, const float* DSC, const bf16* ZG, const float* gnorm, bf16* OG, float* state_out, int bid, int G, int tid) {
;     ...
; #pragma unroll
;             for (int vt = 0; vt < 8; ++vt) {
;                 f32x4 acc = *(const f32x4*)(OL + ((((size_t)(h * 16 + sc) * 32 + c) * 8 + vt) * 64 + lane) * 4);
; #pragma unroll
;                 for (int s = 0; s < 4; ++s) acc = MFMA16(a[s], *(const LAS bf16x8*)(lds + HC_SINT + (16 * vt + lr) * 272 + 64 * s + 16 * g), acc);
;                 o[vt] = acc;
; #pragma unroll
;                 for (int i = 0; i < 4; ++i) ssq[i] += acc[i] * acc[i];
;             }
;             float rs[4];
; #pragma unroll
;             for (int i = 0; i < 4; ++i) rs[i] = rsqrtf(grp16_sum(ssq[i]) * (1.f / 128.f) + EPS);
; #pragma unroll
	v_mfma_f32_16x16x32_bf16 v[86:89], v[176:179], v[8:11], v[86:89]
	ds_read_b128 v[8:11], v74 offset:30592
	ds_read_b128 v[122:125], v74 offset:30656
	s_waitcnt vmcnt(12)
	v_mfma_f32_16x16x32_bf16 v[60:63], v[180:183], v[114:117], v[60:63]
	s_waitcnt lgkmcnt(1)
	v_mfma_f32_16x16x32_bf16 v[90:93], v[176:179], v[8:11], v[94:97]
	v_mfma_f32_16x16x32_bf16 v[8:11], v[180:183], v[82:85], v[0:3]
	s_nop 2
	s_nop 1
	v_mov_b32_e32 v97, v60
	v_add_co_u32_e32 v82, vcc, s23, v64
	v_mfma_f32_16x16x32_bf16 v[0:3], v[180:183], v[102:105], v[78:81]
	v_mov_b32_e32 v103, v63
	v_addc_co_u32_e32 v83, vcc, 0, v65, vcc
	v_mfma_f32_16x16x32_bf16 v[52:55], v[180:183], v[106:109], v[52:55]
	v_mfma_f32_16x16x32_bf16 v[4:7], v[180:183], v[98:101], v[4:7]
	s_nop 3
	v_mov_b32_e32 v84, v0
	s_nop 1
	v_mov_b32_e32 v85, v52
	v_mov_b32_e32 v94, v3
	v_mfma_f32_16x16x32_bf16 v[56:59], v[180:183], v[110:113], v[56:59]
	v_mov_b32_e32 v95, v55
	v_mov_b32_e32 v99, v61
	v_pk_mul_f32 v[84:85], v[84:85], v[84:85]
	v_mfma_f32_16x16x32_bf16 v[78:81], v[180:183], v[118:121], v[86:89]
	v_mul_f32_e64 v94, v94, v94
	v_mul_f32_e64 v95, v95, v95
	s_nop 1
	v_mov_b32_e32 v96, v56
	v_mov_b32_e32 v98, v57
	s_waitcnt lgkmcnt(0)
	v_mfma_f32_16x16x32_bf16 v[12:15], v[180:183], v[122:125], v[90:93]
	v_mov_b32_e32 v86, v1
	v_mov_b32_e32 v87, v53
	v_mov_b32_e32 v104, v78
	v_pk_mul_f32 v[90:91], v[4:5], v[4:5]
	v_mov_b32_e32 v92, v2
	v_mov_b32_e32 v93, v54
	s_nop 1
	v_mov_b32_e32 v105, v12
	v_mov_b32_e32 v106, v79
	v_mov_b32_e32 v107, v13
	v_pk_mul_f32 v[86:87], v[86:87], v[86:87]
	v_pk_mul_f32 v[88:89], v[6:7], v[6:7]
	v_pk_fma_f32 v[90:91], v[8:9], v[8:9], v[90:91]
	v_pk_mul_f32 v[92:93], v[92:93], v[92:93]
	v_pk_mul_f32 v[96:97], v[96:97], v[96:97]
	v_pk_mul_f32 v[98:99], v[98:99], v[98:99]
	v_pk_mul_f32 v[104:105], v[104:105], v[104:105]
	v_pk_mul_f32 v[106:107], v[106:107], v[106:107]
	v_mov_b32_e32 v112, v86
	v_mov_b32_e32 v113, v84
	v_mov_b32_e32 v100, v58
	v_mov_b32_e32 v101, v62
	v_mov_b32_e32 v102, v59
	v_pk_fma_f32 v[88:89], v[10:11], v[10:11], v[88:89]
	v_mov_b32_e32 v84, v87
	v_mov_b32_e32 v86, v98
	v_mov_b32_e32 v87, v96
	v_mov_b32_e32 v96, v99
	v_mov_b32_e32 v98, v106
	v_mov_b32_e32 v99, v104
	v_mov_b32_e32 v104, v107
	v_mov_b32_e32 v106, v94
	v_mov_b32_e32 v107, v92
	v_pk_add_f32 v[90:91], v[90:91], v[112:113] op_sel:[1,0] op_sel_hi:[0,1]
	v_pk_mul_f32 v[100:101], v[100:101], v[100:101]
	v_pk_mul_f32 v[102:103], v[102:103], v[102:103]
	v_mov_b32_e32 v92, v95
	v_pk_add_f32 v[88:89], v[88:89], v[106:107] op_sel:[1,0] op_sel_hi:[0,1]
	v_pk_add_f32 v[84:85], v[90:91], v[84:85]
	v_mov_b32_e32 v108, v80
	v_mov_b32_e32 v109, v14
	v_mov_b32_e32 v110, v81
	v_mov_b32_e32 v111, v15
	v_mov_b32_e32 v94, v102
	v_mov_b32_e32 v95, v100
	v_pk_add_f32 v[88:89], v[88:89], v[92:93]
	v_pk_add_f32 v[84:85], v[84:85], v[86:87]
	v_pk_mul_f32 v[108:109], v[108:109], v[108:109]
	v_pk_mul_f32 v[110:111], v[110:111], v[110:111]
	v_mov_b32_e32 v100, v103
	v_pk_add_f32 v[86:87], v[88:89], v[94:95]
	v_pk_add_f32 v[84:85], v[84:85], v[96:97]
	v_mov_b32_e32 v102, v110
	v_mov_b32_e32 v103, v108
	v_pk_add_f32 v[86:87], v[86:87], v[100:101]
	v_pk_add_f32 v[84:85], v[84:85], v[98:99]
	v_mov_b32_e32 v108, v111
	v_pk_add_f32 v[86:87], v[86:87], v[102:103]
	v_pk_add_f32 v[84:85], v[84:85], v[104:105]
	v_pk_add_f32 v[86:87], v[86:87], v[108:109]
	ds_bpermute_b32 v89, v48, v85
	ds_bpermute_b32 v88, v48, v84
	ds_bpermute_b32 v91, v48, v87
	ds_bpermute_b32 v90, v48, v86
	s_waitcnt lgkmcnt(2)
	v_pk_add_f32 v[84:85], v[84:85], v[88:89]
	ds_bpermute_b32 v89, v49, v85
	s_waitcnt lgkmcnt(1)
	v_pk_add_f32 v[86:87], v[86:87], v[90:91]
	ds_bpermute_b32 v88, v49, v84
	ds_bpermute_b32 v91, v49, v87
	ds_bpermute_b32 v90, v49, v86
	s_waitcnt lgkmcnt(2)
	v_pk_add_f32 v[84:85], v[84:85], v[88:89]
	ds_bpermute_b32 v89, v50, v85
	s_waitcnt lgkmcnt(1)
	v_pk_add_f32 v[86:87], v[86:87], v[90:91]
	ds_bpermute_b32 v88, v50, v84
	ds_bpermute_b32 v91, v50, v87
	ds_bpermute_b32 v90, v50, v86
	s_waitcnt lgkmcnt(2)
	v_pk_add_f32 v[84:85], v[84:85], v[88:89]
	ds_bpermute_b32 v89, v51, v85
	s_waitcnt lgkmcnt(1)
	v_pk_add_f32 v[86:87], v[86:87], v[90:91]
	ds_bpermute_b32 v88, v51, v84
	ds_bpermute_b32 v91, v51, v87
	ds_bpermute_b32 v90, v51, v86
	s_waitcnt lgkmcnt(2)
	v_pk_add_f32 v[84:85], v[84:85], v[88:89]
	s_nop 0
	v_pk_fma_f32 v[84:85], v[84:85], s[18:19], v[46:47] op_sel_hi:[1,0,0]
	s_waitcnt lgkmcnt(0)
	v_pk_add_f32 v[86:87], v[86:87], v[90:91]
	v_cmp_gt_f32_e64 s[8:9], s21, v85
	v_pk_fma_f32 v[46:47], v[86:87], s[18:19], v[46:47] op_sel_hi:[1,0,0]
	v_mul_f32_e32 v86, 0x4b800000, v85
	v_mul_f32_e32 v87, 0x4b800000, v84
	v_cmp_gt_f32_e32 vcc, s21, v84
	v_mul_f32_e32 v88, 0x4b800000, v47
	v_mul_f32_e32 v89, 0x4b800000, v46
	v_cmp_gt_f32_e64 s[4:5], s21, v46
	v_cmp_gt_f32_e64 s[6:7], s21, v47
	v_cndmask_b32_e64 v85, v85, v86, s[8:9]
	v_cndmask_b32_e32 v84, v84, v87, vcc
	v_cndmask_b32_e64 v47, v47, v88, s[6:7]
	v_cndmask_b32_e64 v46, v46, v89, s[4:5]
	v_rsq_f32_e32 v85, v85
	v_rsq_f32_e32 v84, v84
	v_rsq_f32_e32 v47, v47
	v_rsq_f32_e32 v46, v46
	v_mul_f32_e32 v86, 0x45800000, v85
	v_mul_f32_e32 v87, 0x45800000, v84
	v_mul_f32_e32 v88, 0x45800000, v47
	v_mul_f32_e32 v89, 0x45800000, v46
	v_cndmask_b32_e64 v85, v85, v86, s[8:9]
	v_cndmask_b32_e32 v84, v84, v87, vcc
	v_cndmask_b32_e64 v47, v47, v88, s[6:7]
	v_cndmask_b32_e64 v46, v46, v89, s[4:5]
	v_mul_f32_e32 v8, v8, v85
	v_mul_f32_e32 v4, v4, v85
	v_mul_f32_e32 v9, v9, v84
	v_mul_f32_e32 v10, v10, v47
	v_mul_f32_e32 v11, v11, v46
	v_mul_f32_e32 v5, v5, v84
	v_mul_f32_e32 v6, v6, v47
	v_mul_f32_e32 v7, v7, v46
	v_mul_f32_e32 v0, v0, v85
	v_mul_f32_e32 v1, v1, v84
	v_mul_f32_e32 v2, v2, v47
	v_mul_f32_e32 v3, v3, v46
	v_mul_f32_e32 v52, v52, v85
	v_mul_f32_e32 v53, v53, v84
	v_mul_f32_e32 v54, v54, v47
	v_mul_f32_e32 v55, v55, v46
	v_mul_f32_e32 v56, v56, v85
	v_mul_f32_e32 v57, v57, v84
	v_mul_f32_e32 v58, v58, v47
	v_mul_f32_e32 v59, v59, v46
	v_mul_f32_e32 v60, v60, v85
	v_mul_f32_e32 v61, v61, v84
	v_mul_f32_e32 v62, v62, v47
	v_mul_f32_e32 v63, v63, v46
	v_mul_f32_e32 v78, v78, v85
	v_mul_f32_e32 v79, v79, v84
	v_mul_f32_e32 v80, v80, v47
	v_mul_f32_e32 v81, v81, v46
	v_mul_f32_e32 v12, v12, v85
	v_mul_f32_e32 v13, v13, v84
	v_mul_f32_e32 v14, v14, v47
	v_mul_f32_e32 v15, v15, v46
	s_waitcnt vmcnt(11)
; #define LAS __attribute__((address_space(3)))
; DI float bf2f(unsigned b) { return __uint_as_float(b << 16); }
; #define LDS_WAIT() asm volatile("s_waitcnt lgkmcnt(0)" ::: "memory")
; DI bf16x8 pack8(const f32x4& a, const f32x4& b) { v4u w; w.x = pk2(a[0], a[1]); w.y = pk2(a[2], a[3]); w.z = pk2(b[0], b[1]); w.w = pk2(b[2], b[3]); return __builtin_bit_cast(bf16x8, w); }
; DI void hgrn_passC(LAS unsigned char* lds, const bf16* QG, const float* OL, const float* DS, const float* DSC, const bf16* ZG, const float* gnorm, bf16* OG, float* state_out, int bid, int G, int tid) {
;     ...
;             for (int vt = 0; vt < 8; ++vt) { const float gn = gnorm[16 * vt + lr];
; #pragma unroll
;                 for (int i = 0; i < 4; ++i) stg[(4 * g + i) * 132 + 16 * vt + lr] = o[vt][i] * rs[i] * gn; }
;             LDS_WAIT(); asm volatile("" ::: "memory");
; #pragma unroll
;             for (int it = 0; it < 4; ++it) {
;                 const int ci = lane + 64 * it, r = ci >> 4, ch = ci & 15; const size_t go = (size_t)(t0 + 16 * c + r) * D + cb + 8 * ch;
;                 const f32x4 x0 = *(const LAS f32x4*)(stg + r * 132 + 8 * ch), x1 = *(const LAS f32x4*)(stg + r * 132 + 8 * ch + 4);
;                 const v4u gt = *(const v4u*)(ZG + go);
;                 f32x4 y0, y1; y0[0] = x0[0] * bf2f(gt.x & 0xffffu); y0[1] = x0[1] * bf2f(gt.x >> 16); y0[2] = x0[2] * bf2f(gt.y & 0xffffu); y0[3] = x0[3] * bf2f(gt.y >> 16);
;                 y1[0] = x1[0] * bf2f(gt.z & 0xffffu); y1[1] = x1[1] * bf2f(gt.z >> 16); y1[2] = x1[2] * bf2f(gt.w & 0xffffu); y1[3] = x1[3] * bf2f(gt.w >> 16);
;                 *(bf16x8*)(OG + go) = pack8(y0, y1);
;             }
	v_mul_f32_e32 v8, v8, v184
	s_waitcnt vmcnt(10)
	v_mul_f32_e32 v4, v4, v185
	v_mul_f32_e32 v9, v184, v9
	v_mul_f32_e32 v10, v184, v10
	v_mul_f32_e32 v11, v184, v11
	v_mul_f32_e32 v5, v5, v185
	v_mul_f32_e32 v6, v185, v6
	v_mul_f32_e32 v7, v185, v7
	s_waitcnt vmcnt(9)
	v_mul_f32_e32 v0, v0, v186
	v_mul_f32_e32 v1, v1, v186
	v_mul_f32_e32 v2, v2, v186
	v_mul_f32_e32 v3, v3, v186
	s_waitcnt vmcnt(8)
	v_mul_f32_e32 v46, v52, v187
	v_mul_f32_e32 v47, v53, v187
	v_mul_f32_e32 v52, v54, v187
	v_mul_f32_e32 v53, v55, v187
	s_waitcnt vmcnt(7)
	v_mul_f32_e32 v54, v56, v188
	v_mul_f32_e32 v55, v57, v188
	v_mul_f32_e32 v56, v58, v188
	v_mul_f32_e32 v57, v59, v188
	s_waitcnt vmcnt(6)
	v_mul_f32_e32 v58, v60, v189
	v_mul_f32_e32 v59, v61, v189
	v_mul_f32_e32 v60, v62, v189
	v_mul_f32_e32 v61, v63, v189
	s_waitcnt vmcnt(5)
	v_mul_f32_e32 v62, v78, v190
	v_mul_f32_e32 v63, v79, v190
	v_mul_f32_e32 v78, v80, v190
	v_mul_f32_e32 v79, v81, v190
	s_waitcnt vmcnt(4)
	v_mul_f32_e32 v12, v12, v191
	v_mul_f32_e32 v13, v13, v191
	v_mul_f32_e32 v14, v14, v191
	v_mul_f32_e32 v15, v15, v191
	ds_write2_b32 v126, v8, v4 offset1:16
	ds_write2_b32 v126, v9, v5 offset0:132 offset1:148
	ds_write2_b32 v127, v10, v6 offset0:8 offset1:24
	ds_write2_b32 v127, v11, v7 offset0:140 offset1:156
	ds_write2_b32 v126, v0, v46 offset0:32 offset1:48
	ds_write2_b32 v126, v1, v47 offset0:164 offset1:180
	ds_write2_b32 v127, v2, v52 offset0:40 offset1:56
	ds_write2_b32 v127, v3, v53 offset0:172 offset1:188
	ds_write2_b32 v126, v54, v58 offset0:64 offset1:80
	ds_write2_b32 v126, v55, v59 offset0:196 offset1:212
	ds_write2_b32 v127, v56, v60 offset0:72 offset1:88
	ds_write2_b32 v127, v57, v61 offset0:204 offset1:220
	ds_write2_b32 v126, v62, v12 offset0:96 offset1:112
	ds_write2_b32 v126, v63, v13 offset0:228 offset1:244
	ds_write2_b32 v127, v78, v14 offset0:104 offset1:120
	ds_write2_b32 v127, v79, v15 offset0:236 offset1:252
	s_waitcnt lgkmcnt(0)
	ds_read_b128 v[4:7], v76 offset:34816
	ds_read_b128 v[8:11], v76 offset:34832
	v_add_co_u32_e32 v14, vcc, s29, v64
	v_lshl_add_u64 v[12:13], s[10:11], 0, v[42:43]
	s_nop 0
	v_addc_co_u32_e32 v15, vcc, 0, v65, vcc
	v_add_co_u32_e32 v46, vcc, s23, v12
	v_lshl_add_u64 v[42:43], v[42:43], 0, s[38:39]
	s_nop 0
	v_addc_co_u32_e32 v47, vcc, 0, v13, vcc
	v_add_co_u32_e32 v12, vcc, s29, v12
	s_waitcnt vmcnt(3)
	v_lshlrev_b32_e32 v52, 16, v200
	v_and_b32_e32 v53, 0xffff0000, v200
	v_lshlrev_b32_e32 v0, 16, v201
	v_and_b32_e32 v1, 0xffff0000, v201
	v_lshlrev_b32_e32 v54, 16, v202
	v_and_b32_e32 v55, 0xffff0000, v202
	v_lshlrev_b32_e32 v2, 16, v203
	v_and_b32_e32 v3, 0xffff0000, v203
	s_waitcnt lgkmcnt(1)
	v_pk_mul_f32 v[4:5], v[4:5], v[52:53]
	v_pk_mul_f32 v[6:7], v[6:7], v[0:1]
	s_waitcnt lgkmcnt(0)
	v_pk_mul_f32 v[8:9], v[8:9], v[54:55]
	v_pk_mul_f32 v[10:11], v[10:11], v[2:3]
	v_cvt_pk_bf16_f32 v0, v4, v5
	v_cvt_pk_bf16_f32 v1, v6, v7
	v_cvt_pk_bf16_f32 v2, v8, v9
	v_cvt_pk_bf16_f32 v3, v10, v11
	global_store_dwordx4 v[14:15], v[0:3], off
	ds_read_b128 v[4:7], v76 offset:36928
	ds_read_b128 v[8:11], v76 offset:36944
	v_lshl_add_u64 v[14:15], s[10:11], 0, v[40:41]
	v_addc_co_u32_e32 v13, vcc, 0, v13, vcc
	v_add_co_u32_e32 v46, vcc, s23, v14
	v_lshl_add_u64 v[40:41], v[40:41], 0, s[38:39]
	s_nop 0
	v_addc_co_u32_e32 v47, vcc, 0, v15, vcc
	v_add_co_u32_e32 v14, vcc, s29, v14
	s_waitcnt vmcnt(3)
	v_lshlrev_b32_e32 v52, 16, v204
	v_and_b32_e32 v53, 0xffff0000, v204
	v_lshlrev_b32_e32 v0, 16, v205
	v_and_b32_e32 v1, 0xffff0000, v205
	v_lshlrev_b32_e32 v54, 16, v206
	v_and_b32_e32 v55, 0xffff0000, v206
	v_lshlrev_b32_e32 v2, 16, v207
	v_and_b32_e32 v3, 0xffff0000, v207
	s_waitcnt lgkmcnt(1)
	v_pk_mul_f32 v[4:5], v[4:5], v[52:53]
	v_pk_mul_f32 v[6:7], v[6:7], v[0:1]
	s_waitcnt lgkmcnt(0)
	v_pk_mul_f32 v[8:9], v[8:9], v[54:55]
	v_pk_mul_f32 v[10:11], v[10:11], v[2:3]
	v_cvt_pk_bf16_f32 v0, v4, v5
	v_cvt_pk_bf16_f32 v1, v6, v7
	v_cvt_pk_bf16_f32 v2, v8, v9
	v_cvt_pk_bf16_f32 v3, v10, v11
	global_store_dwordx4 v[12:13], v[0:3], off
	ds_read_b128 v[4:7], v76 offset:39040
	ds_read_b128 v[8:11], v76 offset:39056
	v_lshl_add_u64 v[12:13], s[10:11], 0, v[38:39]
	v_addc_co_u32_e32 v15, vcc, 0, v15, vcc
	v_add_co_u32_e32 v46, vcc, s23, v12
	v_lshl_add_u64 v[38:39], v[38:39], 0, s[38:39]
	s_nop 0
	v_addc_co_u32_e32 v47, vcc, 0, v13, vcc
	v_add_co_u32_e32 v12, vcc, s29, v12
	s_waitcnt vmcnt(3)
	v_lshlrev_b32_e32 v52, 16, v208
	v_and_b32_e32 v53, 0xffff0000, v208
	v_lshlrev_b32_e32 v0, 16, v209
	v_and_b32_e32 v1, 0xffff0000, v209
	v_lshlrev_b32_e32 v54, 16, v210
	v_and_b32_e32 v55, 0xffff0000, v210
	v_lshlrev_b32_e32 v2, 16, v211
	v_and_b32_e32 v3, 0xffff0000, v211
	s_waitcnt lgkmcnt(1)
	v_pk_mul_f32 v[4:5], v[4:5], v[52:53]
	v_pk_mul_f32 v[6:7], v[6:7], v[0:1]
	s_waitcnt lgkmcnt(0)
	v_pk_mul_f32 v[8:9], v[8:9], v[54:55]
	v_pk_mul_f32 v[10:11], v[10:11], v[2:3]
	v_cvt_pk_bf16_f32 v0, v4, v5
	v_cvt_pk_bf16_f32 v1, v6, v7
	v_cvt_pk_bf16_f32 v2, v8, v9
	v_cvt_pk_bf16_f32 v3, v10, v11
	global_store_dwordx4 v[14:15], v[0:3], off
	ds_read_b128 v[4:7], v76 offset:41152
	ds_read_b128 v[8:11], v76 offset:41168
	v_addc_co_u32_e32 v13, vcc, 0, v13, vcc
	s_waitcnt vmcnt(3)
	v_lshlrev_b32_e32 v14, 16, v212
	v_and_b32_e32 v15, 0xffff0000, v212
	v_lshlrev_b32_e32 v0, 16, v213
	v_and_b32_e32 v1, 0xffff0000, v213
	v_lshlrev_b32_e32 v46, 16, v214
	v_and_b32_e32 v47, 0xffff0000, v214
	v_lshlrev_b32_e32 v2, 16, v215
	v_and_b32_e32 v3, 0xffff0000, v215
	s_waitcnt lgkmcnt(1)
	v_pk_mul_f32 v[4:5], v[4:5], v[14:15]
	v_pk_mul_f32 v[6:7], v[6:7], v[0:1]
	s_waitcnt lgkmcnt(0)
	v_pk_mul_f32 v[8:9], v[8:9], v[46:47]
	v_pk_mul_f32 v[10:11], v[10:11], v[2:3]
	v_cvt_pk_bf16_f32 v0, v4, v5
	v_cvt_pk_bf16_f32 v1, v6, v7
	v_cvt_pk_bf16_f32 v2, v8, v9
	v_cvt_pk_bf16_f32 v3, v10, v11
	global_store_dwordx4 v[12:13], v[0:3], off
	s_waitcnt lgkmcnt(0)
	s_cbranch_scc0 .LBB0_461
	s_branch .LBB0_449
